# combo + non-temporal (nt) hint on the read-once LayerNorm row loads
# baseline (speedup 1.0000x reference)
; __device__ __forceinline__ float bflo(unsigned w) { return __uint_as_float(w << 16); }
; __device__ __forceinline__ float bfhi(unsigned w) { return __uint_as_float(w & 0xffff0000u); }
; __device__ __forceinline__ void ln_rows(const bf16* Yb, const float* g, const float* bt, float* outf, bf16* outb, int gw, int NGW, int lane) {
;     u32x4 nx[4];
;     if (gw < M) { const u32x4* yr = (const u32x4*)(Yb + (size_t)gw * D) + lane;
; #pragma unroll
;         for (int j = 0; j < 4; ++j) nx[j] = yr[64 * j]; }
;     for (int row = gw; row < M; row += NGW) {
;         float v[4][8]; float s = 0.f;
; #pragma unroll
;         for (int j = 0; j < 4; ++j) { const u32x4 w = nx[j]; v[j][0] = bflo(w.x); v[j][1] = bfhi(w.x); v[j][2] = bflo(w.y); v[j][3] = bfhi(w.y); v[j][4] = bflo(w.z); v[j][5] = bfhi(w.z); v[j][6] = bflo(w.w); v[j][7] = bfhi(w.w);
;             s += ((v[j][0] + v[j][1]) + (v[j][2] + v[j][3])) + ((v[j][4] + v[j][5]) + (v[j][6] + v[j][7])); }
;         if (row + NGW < M) { const u32x4* yr = (const u32x4*)(Yb + (size_t)(row + NGW) * D) + lane;
; #pragma unroll
;             for (int j = 0; j < 4; ++j) nx[j] = yr[64 * j]; }
;         const float mean = wave_sum(s) * (1.f / D); float s2 = 0.f;
; #pragma unroll
;         for (int j = 0; j < 4; ++j)
; #pragma unroll
;             for (int i = 0; i < 8; ++i) { v[j][i] -= mean; s2 += v[j][i] * v[j][i]; }
;         const float rstd = 1.f / sqrtf(wave_sum(s2) * (1.f / D) + LN_EPS);
; #pragma unroll
;         for (int j = 0; j < 4; ++j) { const int col = 8 * (lane + 64 * j);
;             const f32x4 g0 = *(const f32x4*)(g + col), g1 = *(const f32x4*)(g + col + 4), b0 = *(const f32x4*)(bt + col), b1 = *(const f32x4*)(bt + col + 4);
.LBB0_454:
	s_cmp_lt_i32 s44, 5
	s_cselect_b64 s[6:7], -1, 0
	s_and_b64 s[6:7], s[6:7], s[4:5]
	s_cmp_lt_i32 s38, 0x8000
	s_cselect_b64 s[10:11], -1, 0
	s_and_b64 s[4:5], s[6:7], s[10:11]
	s_andn2_b64 vcc, exec, s[4:5]
	v_lshlrev_b32_e32 v136, 4, v171
	v_mbcnt_lo_u32_b32 v172, -1, 0
	v_lshlrev_b32_e32 v138, 5, v171
	s_cbranch_vccnz .LBB0_459
	s_ashr_i32 s39, s38, 31
	s_lshl_b64 s[4:5], s[38:39], 12
	s_waitcnt lgkmcnt(0)
	s_add_u32 s12, s8, s4
	s_addc_u32 s13, s9, s5
	global_load_dwordx4 v[28:31], v136, s[12:13] nt
	global_load_dwordx4 v[24:27], v136, s[12:13] offset:1024 nt
	global_load_dwordx4 v[20:23], v136, s[12:13] offset:2048 nt
	global_load_dwordx4 v[16:19], v136, s[12:13] offset:3072 nt
	v_mbcnt_hi_u32_b32 v0, -1, v172
	v_and_b32_e32 v1, 64, v0
	v_add_u32_e32 v1, 64, v1
	v_xor_b32_e32 v2, 1, v0
	v_cmp_lt_i32_e32 vcc, v2, v1
	s_load_dwordx4 s[12:15], s[0:1], 0x88
	v_mov_b32_e32 v137, 0
	v_cndmask_b32_e32 v2, v0, v2, vcc
	v_lshlrev_b32_e32 v53, 2, v2
	v_xor_b32_e32 v2, 2, v0
	v_cmp_lt_i32_e32 vcc, v2, v1
	v_mov_b32_e32 v139, v137
	s_waitcnt lgkmcnt(0)
	v_lshl_add_u64 v[32:33], s[12:13], 0, v[138:139]
	v_cndmask_b32_e32 v2, v0, v2, vcc
	v_lshlrev_b32_e32 v54, 2, v2
	v_xor_b32_e32 v2, 4, v0
	v_cmp_lt_i32_e32 vcc, v2, v1
	v_lshl_add_u64 v[34:35], s[14:15], 0, v[138:139]
	s_movk_i32 s3, 0x7fff
	v_cndmask_b32_e32 v2, v0, v2, vcc
	v_lshlrev_b32_e32 v55, 2, v2
	v_xor_b32_e32 v2, 8, v0
	v_cmp_lt_i32_e32 vcc, v2, v1
	s_mov_b32 s20, 0xffff0000
	v_mov_b32_e32 v59, 0x3727c5ac
	v_cndmask_b32_e32 v2, v0, v2, vcc
	v_lshlrev_b32_e32 v56, 2, v2
	v_xor_b32_e32 v2, 16, v0
	v_cmp_lt_i32_e32 vcc, v2, v1
	s_mov_b32 s21, 0xf800000
	v_mov_b32_e32 v60, 0x260
	v_cndmask_b32_e32 v2, v0, v2, vcc
	v_lshlrev_b32_e32 v57, 2, v2
	v_xor_b32_e32 v2, 32, v0
	v_cmp_lt_i32_e32 vcc, v2, v1
	v_mov_b32_e32 v1, v137
	s_mov_b32 s22, 0x25800000
	v_cndmask_b32_e32 v0, v0, v2, vcc
	v_lshlrev_b32_e32 v58, 2, v0
	v_or_b32_e32 v0, 0x1000, v138
	v_lshl_add_u64 v[36:37], s[12:13], 0, v[0:1]
	v_lshl_add_u64 v[38:39], s[14:15], 0, v[0:1]
	v_or_b32_e32 v0, 0x1800, v138
	v_lshl_add_u64 v[40:41], s[12:13], 0, v[0:1]
	s_add_u32 s12, s42, s4
	s_addc_u32 s13, s43, s5
	s_add_i32 s4, s38, s56
	s_ashr_i32 s57, s56, 31
	s_ashr_i32 s5, s4, 31
	v_lshl_add_u64 v[42:43], s[14:15], 0, v[0:1]
	s_lshl_b64 s[14:15], s[56:57], 12
	s_lshl_b64 s[4:5], s[4:5], 12
	s_add_u32 s16, s42, s4
	s_addc_u32 s17, s43, s5
	s_mov_b32 s23, s38
	global_load_dwordx4 v[176:179], v[32:33], off
	global_load_dwordx4 v[184:187], v[34:35], off
	global_load_dwordx4 v[180:183], v[32:33], off offset:16
	global_load_dwordx4 v[188:191], v[34:35], off offset:16
	global_load_dwordx4 v[192:195], v[32:33], off offset:2048
	global_load_dwordx4 v[200:203], v[34:35], off offset:2048
	global_load_dwordx4 v[196:199], v[32:33], off offset:2064
	global_load_dwordx4 v[204:207], v[34:35], off offset:2064
	global_load_dwordx4 v[208:211], v[36:37], off
	global_load_dwordx4 v[216:219], v[38:39], off
	global_load_dwordx4 v[212:215], v[36:37], off offset:16
	global_load_dwordx4 v[220:223], v[38:39], off offset:16
	global_load_dwordx4 v[224:227], v[40:41], off
	global_load_dwordx4 v[232:235], v[42:43], off
	global_load_dwordx4 v[228:231], v[40:41], off offset:16
	global_load_dwordx4 v[236:239], v[42:43], off offset:16
	s_mov_b32 s98, 0
	s_add_i32 s99, s38, s56
	s_cmpk_gt_i32 s99, 0x7fff
	s_cbranch_scc1 .Lln1_pre_done
	v_lshl_add_u64 v[124:125], s[16:17], 0, v[136:137]
	v_add_co_u32_e32 v124, vcc, 0x35800000, v124
	s_nop 1
	v_addc_co_u32_e32 v125, vcc, 0, v125, vcc
	global_load_dwordx4 v[4:7], v[124:125], off nt
	global_load_dwordx4 v[8:11], v[124:125], off offset:1024 nt
	global_load_dwordx4 v[12:15], v[124:125], off offset:2048 nt
	global_load_dwordx4 v[0:3], v[124:125], off offset:3072 nt
	s_add_u32 s16, s16, s14
	s_addc_u32 s17, s17, s15

; __device__ __forceinline__ float bflo(unsigned w) { return __uint_as_float(w << 16); }
; __device__ __forceinline__ float bfhi(unsigned w) { return __uint_as_float(w & 0xffff0000u); }
; __device__ __forceinline__ void ln_rows(const bf16* Yb, const float* g, const float* bt, float* outf, bf16* outb, int gw, int NGW, int lane) {
;     ...
;     for (int row = gw; row < M; row += NGW) {
;         float v[4][8]; float s = 0.f;
; #pragma unroll
;         for (int j = 0; j < 4; ++j) { const u32x4 w = nx[j]; v[j][0] = bflo(w.x); v[j][1] = bfhi(w.x); v[j][2] = bflo(w.y); v[j][3] = bfhi(w.y); v[j][4] = bflo(w.z); v[j][5] = bfhi(w.z); v[j][6] = bflo(w.w); v[j][7] = bfhi(w.w);
;             s += ((v[j][0] + v[j][1]) + (v[j][2] + v[j][3])) + ((v[j][4] + v[j][5]) + (v[j][6] + v[j][7])); }
;         if (row + NGW < M) { const u32x4* yr = (const u32x4*)(Yb + (size_t)(row + NGW) * D) + lane;
; #pragma unroll
;             for (int j = 0; j < 4; ++j) nx[j] = yr[64 * j]; }
.LBB0_457:
	s_add_i32 s23, s23, s56
	s_cmpk_gt_i32 s23, 0x7fff
	s_cselect_b64 s[18:19], -1, 0
	s_xor_b32 s98, s98, 1
	s_add_i32 s99, s23, s56
	s_cmpk_gt_i32 s99, 0x7fff
	s_cbranch_scc1 .LBB0_456
	v_lshl_add_u64 v[124:125], s[16:17], 0, v[136:137]
	v_add_co_u32_e32 v124, vcc, 0x35800000, v124
	s_nop 1
	v_addc_co_u32_e32 v125, vcc, 0, v125, vcc
	s_cmp_eq_u32 s98, 0
	s_cbranch_scc1 .Lln1_pfN1
	global_load_dwordx4 v[108:111], v[124:125], off nt
	global_load_dwordx4 v[112:115], v[124:125], off offset:1024 nt
	global_load_dwordx4 v[116:119], v[124:125], off offset:2048 nt
	global_load_dwordx4 v[120:123], v[124:125], off offset:3072 nt
	s_branch .LBB0_456
.Lln1_pfN1:
	global_load_dwordx4 v[4:7], v[124:125], off nt
	global_load_dwordx4 v[8:11], v[124:125], off offset:1024 nt
	global_load_dwordx4 v[12:15], v[124:125], off offset:2048 nt
	global_load_dwordx4 v[0:3], v[124:125], off offset:3072 nt
	s_branch .LBB0_456

; __device__ __forceinline__ float bflo(unsigned w) { return __uint_as_float(w << 16); }
; __device__ __forceinline__ float bfhi(unsigned w) { return __uint_as_float(w & 0xffff0000u); }
; __device__ __forceinline__ void ln_rows(const bf16* Yb, const float* g, const float* bt, float* outf, bf16* outb, int gw, int NGW, int lane) {
;     u32x4 nx[4];
;     if (gw < M) { const u32x4* yr = (const u32x4*)(Yb + (size_t)gw * D) + lane;
; #pragma unroll
;         for (int j = 0; j < 4; ++j) nx[j] = yr[64 * j]; }
;     for (int row = gw; row < M; row += NGW) {
;         float v[4][8]; float s = 0.f;
; #pragma unroll
;         for (int j = 0; j < 4; ++j) { const u32x4 w = nx[j]; v[j][0] = bflo(w.x); v[j][1] = bfhi(w.x); v[j][2] = bflo(w.y); v[j][3] = bfhi(w.y); v[j][4] = bflo(w.z); v[j][5] = bfhi(w.z); v[j][6] = bflo(w.w); v[j][7] = bfhi(w.w);
;             s += ((v[j][0] + v[j][1]) + (v[j][2] + v[j][3])) + ((v[j][4] + v[j][5]) + (v[j][6] + v[j][7])); }
;         if (row + NGW < M) { const u32x4* yr = (const u32x4*)(Yb + (size_t)(row + NGW) * D) + lane;
; #pragma unroll
;             for (int j = 0; j < 4; ++j) nx[j] = yr[64 * j]; }
;         const float mean = wave_sum(s) * (1.f / D); float s2 = 0.f;
; #pragma unroll
;         for (int j = 0; j < 4; ++j)
; #pragma unroll
;             for (int i = 0; i < 8; ++i) { v[j][i] -= mean; s2 += v[j][i] * v[j][i]; }
;         const float rstd = 1.f / sqrtf(wave_sum(s2) * (1.f / D) + LN_EPS);
; #pragma unroll
;         for (int j = 0; j < 4; ++j) { const int col = 8 * (lane + 64 * j);
;             const f32x4 g0 = *(const f32x4*)(g + col), g1 = *(const f32x4*)(g + col + 4), b0 = *(const f32x4*)(bt + col), b1 = *(const f32x4*)(bt + col + 4);
.LBB0_667:
	s_cmp_lt_i32 s44, 8
	s_cselect_b64 s[6:7], -1, 0
	s_and_b64 s[6:7], s[6:7], s[4:5]
	s_and_b64 s[4:5], s[6:7], s[10:11]
	s_andn2_b64 vcc, exec, s[4:5]
	s_cbranch_vccnz .LBB0_672
	s_ashr_i32 s39, s38, 31
	s_lshl_b64 s[4:5], s[38:39], 12
	s_add_u32 s12, s8, s4
	s_addc_u32 s13, s9, s5
	global_load_dwordx4 v[28:31], v136, s[12:13] nt
	global_load_dwordx4 v[24:27], v136, s[12:13] offset:1024 nt
	global_load_dwordx4 v[20:23], v136, s[12:13] offset:2048 nt
	global_load_dwordx4 v[16:19], v136, s[12:13] offset:3072 nt
	v_mbcnt_hi_u32_b32 v0, -1, v172
	v_and_b32_e32 v1, 64, v0
	v_add_u32_e32 v1, 64, v1
	v_xor_b32_e32 v2, 1, v0
	v_cmp_lt_i32_e32 vcc, v2, v1
	s_load_dwordx4 s[12:15], s[0:1], 0xb0
	v_mov_b32_e32 v137, 0
	v_cndmask_b32_e32 v2, v0, v2, vcc
	v_lshlrev_b32_e32 v53, 2, v2
	v_xor_b32_e32 v2, 2, v0
	v_cmp_lt_i32_e32 vcc, v2, v1
	v_mov_b32_e32 v139, v137
	s_waitcnt lgkmcnt(0)
	v_lshl_add_u64 v[32:33], s[12:13], 0, v[138:139]
	v_cndmask_b32_e32 v2, v0, v2, vcc
	v_lshlrev_b32_e32 v54, 2, v2
	v_xor_b32_e32 v2, 4, v0
	v_cmp_lt_i32_e32 vcc, v2, v1
	v_lshl_add_u64 v[34:35], s[14:15], 0, v[138:139]
	s_movk_i32 s3, 0x7fff
	v_cndmask_b32_e32 v2, v0, v2, vcc
	v_lshlrev_b32_e32 v55, 2, v2
	v_xor_b32_e32 v2, 8, v0
	v_cmp_lt_i32_e32 vcc, v2, v1
	s_mov_b32 s20, 0xffff0000
	v_mov_b32_e32 v59, 0x3727c5ac
	v_cndmask_b32_e32 v2, v0, v2, vcc
	v_lshlrev_b32_e32 v56, 2, v2
	v_xor_b32_e32 v2, 16, v0
	v_cmp_lt_i32_e32 vcc, v2, v1
	s_mov_b32 s21, 0xf800000
	v_mov_b32_e32 v60, 0x260
	v_cndmask_b32_e32 v2, v0, v2, vcc
	v_lshlrev_b32_e32 v57, 2, v2
	v_xor_b32_e32 v2, 32, v0
	v_cmp_lt_i32_e32 vcc, v2, v1
	v_mov_b32_e32 v1, v137
	s_mov_b32 s22, 0x25800000
	v_cndmask_b32_e32 v0, v0, v2, vcc
	v_lshlrev_b32_e32 v58, 2, v0
	v_or_b32_e32 v0, 0x1000, v138
	v_lshl_add_u64 v[36:37], s[12:13], 0, v[0:1]
	v_lshl_add_u64 v[38:39], s[14:15], 0, v[0:1]
	v_or_b32_e32 v0, 0x1800, v138
	v_lshl_add_u64 v[40:41], s[12:13], 0, v[0:1]
	s_add_u32 s12, s42, s4
	s_addc_u32 s13, s43, s5
	s_add_i32 s4, s38, s56
	s_ashr_i32 s57, s56, 31
	s_ashr_i32 s5, s4, 31
	v_lshl_add_u64 v[42:43], s[14:15], 0, v[0:1]
	s_lshl_b64 s[14:15], s[56:57], 12
	s_lshl_b64 s[4:5], s[4:5], 12
	s_add_u32 s16, s42, s4
	s_addc_u32 s17, s43, s5
	s_mov_b32 s23, s38
	global_load_dwordx4 v[176:179], v[32:33], off
	global_load_dwordx4 v[184:187], v[34:35], off
	global_load_dwordx4 v[180:183], v[32:33], off offset:16
	global_load_dwordx4 v[188:191], v[34:35], off offset:16
	global_load_dwordx4 v[192:195], v[32:33], off offset:2048
	global_load_dwordx4 v[200:203], v[34:35], off offset:2048
	global_load_dwordx4 v[196:199], v[32:33], off offset:2064
	global_load_dwordx4 v[204:207], v[34:35], off offset:2064
	global_load_dwordx4 v[208:211], v[36:37], off
	global_load_dwordx4 v[216:219], v[38:39], off
	global_load_dwordx4 v[212:215], v[36:37], off offset:16
	global_load_dwordx4 v[220:223], v[38:39], off offset:16
	global_load_dwordx4 v[224:227], v[40:41], off
	global_load_dwordx4 v[232:235], v[42:43], off
	global_load_dwordx4 v[228:231], v[40:41], off offset:16
	global_load_dwordx4 v[236:239], v[42:43], off offset:16
	s_mov_b32 s98, 0
	s_add_i32 s99, s38, s56
	s_cmpk_gt_i32 s99, 0x7fff
	s_cbranch_scc1 .Lln2_pre_done
	v_lshl_add_u64 v[124:125], s[16:17], 0, v[136:137]
	v_add_co_u32_e32 v124, vcc, 0x35800000, v124
	s_nop 1
	v_addc_co_u32_e32 v125, vcc, 0, v125, vcc
	global_load_dwordx4 v[4:7], v[124:125], off nt
	global_load_dwordx4 v[8:11], v[124:125], off offset:1024 nt
	global_load_dwordx4 v[12:15], v[124:125], off offset:2048 nt
	global_load_dwordx4 v[0:3], v[124:125], off offset:3072 nt
	s_add_u32 s16, s16, s14
	s_addc_u32 s17, s17, s15

; __device__ __forceinline__ unsigned pk2(float lo, float hi) { return f2bf(lo) | (f2bf(hi) << 16); }
; __device__ __forceinline__ float bflo(unsigned w) { return __uint_as_float(w << 16); }
; __device__ __forceinline__ float bfhi(unsigned w) { return __uint_as_float(w & 0xffff0000u); }
; __device__ __forceinline__ void ln_rows(const bf16* Yb, const float* g, const float* bt, float* outf, bf16* outb, int gw, int NGW, int lane) {
;     u32x4 nx[4];
;     if (gw < M) { const u32x4* yr = (const u32x4*)(Yb + (size_t)gw * D) + lane;
; #pragma unroll
;         for (int j = 0; j < 4; ++j) nx[j] = yr[64 * j]; }
;     for (int row = gw; row < M; row += NGW) {
;         float v[4][8]; float s = 0.f;
; #pragma unroll
;         for (int j = 0; j < 4; ++j) { const u32x4 w = nx[j]; v[j][0] = bflo(w.x); v[j][1] = bfhi(w.x); v[j][2] = bflo(w.y); v[j][3] = bfhi(w.y); v[j][4] = bflo(w.z); v[j][5] = bfhi(w.z); v[j][6] = bflo(w.w); v[j][7] = bfhi(w.w);
;             s += ((v[j][0] + v[j][1]) + (v[j][2] + v[j][3])) + ((v[j][4] + v[j][5]) + (v[j][6] + v[j][7])); }
;         if (row + NGW < M) { const u32x4* yr = (const u32x4*)(Yb + (size_t)(row + NGW) * D) + lane;
; #pragma unroll
;             for (int j = 0; j < 4; ++j) nx[j] = yr[64 * j]; }
;         const float mean = wave_sum(s) * (1.f / D); float s2 = 0.f;
; #pragma unroll
;         for (int j = 0; j < 4; ++j)
; #pragma unroll
;             for (int i = 0; i < 8; ++i) { v[j][i] -= mean; s2 += v[j][i] * v[j][i]; }
;         const float rstd = 1.f / sqrtf(wave_sum(s2) * (1.f / D) + LN_EPS);
; #pragma unroll
;         for (int j = 0; j < 4; ++j) { const int col = 8 * (lane + 64 * j);
;             const f32x4 g0 = *(const f32x4*)(g + col), g1 = *(const f32x4*)(g + col + 4), b0 = *(const f32x4*)(bt + col), b1 = *(const f32x4*)(bt + col + 4);
;             const f32x4 o0 = (f32x4){v[j][0], v[j][1], v[j][2], v[j][3]} * rstd * g0 + b0, o1 = (f32x4){v[j][4], v[j][5], v[j][6], v[j][7]} * rstd * g1 + b1;
;             if (outf) { *(f32x4*)(outf + (size_t)row * D + col) = o0; *(f32x4*)(outf + (size_t)row * D + col + 4) = o1; }
;             if (outb) { u32x4 w; w.x = pk2(o0[0], o0[1]); w.y = pk2(o0[2], o0[3]); w.z = pk2(o1[0], o1[1]); w.w = pk2(o1[2], o1[3]); *(u32x4*)(outb + (size_t)row * D + col) = w; } }
.LBB0_805:
	s_cmp_lt_i32 s44, 10
	s_cselect_b64 s[4:5], -1, 0
	s_and_b64 s[2:3], s[4:5], s[2:3]
	s_and_b64 s[2:3], s[2:3], s[10:11]
	s_andn2_b64 vcc, exec, s[2:3]
	s_cbranch_vccnz .LBB0_812
	s_ashr_i32 s39, s38, 31
	s_lshl_b64 s[2:3], s[38:39], 12
	s_add_u32 s2, s8, s2
	s_addc_u32 s3, s9, s3
	global_load_dwordx4 v[28:31], v136, s[2:3] nt
	global_load_dwordx4 v[24:27], v136, s[2:3] offset:1024 nt
	global_load_dwordx4 v[20:23], v136, s[2:3] offset:2048 nt
	global_load_dwordx4 v[16:19], v136, s[2:3] offset:3072 nt
	v_mbcnt_hi_u32_b32 v0, -1, v172
	v_and_b32_e32 v1, 64, v0
	v_add_u32_e32 v1, 64, v1
	v_xor_b32_e32 v2, 1, v0
	v_cmp_lt_i32_e32 vcc, v2, v1
	s_load_dwordx4 s[4:7], s[0:1], 0xd8
	s_cmp_lg_u64 s[40:41], 0
	v_cndmask_b32_e32 v2, v0, v2, vcc
	v_lshlrev_b32_e32 v64, 2, v2
	v_xor_b32_e32 v2, 2, v0
	v_cmp_lt_i32_e32 vcc, v2, v1
	v_mov_b32_e32 v137, 0
	s_cselect_b64 s[2:3], -1, 0
	v_cndmask_b32_e32 v2, v0, v2, vcc
	v_lshlrev_b32_e32 v65, 2, v2
	v_xor_b32_e32 v2, 4, v0
	v_cmp_lt_i32_e32 vcc, v2, v1
	s_lshl_b64 s[0:1], s[38:39], 13
	s_add_u32 s0, s40, s0
	v_cndmask_b32_e32 v2, v0, v2, vcc
	v_lshlrev_b32_e32 v66, 2, v2
	v_xor_b32_e32 v2, 8, v0
	v_cmp_lt_i32_e32 vcc, v2, v1
	v_mov_b32_e32 v139, v137
	s_addc_u32 s1, s41, s1
	v_cndmask_b32_e32 v2, v0, v2, vcc
	v_lshlrev_b32_e32 v67, 2, v2
	v_xor_b32_e32 v2, 16, v0
	v_cmp_lt_i32_e32 vcc, v2, v1
	s_ashr_i32 s57, s56, 31
	s_waitcnt lgkmcnt(0)
	v_lshl_add_u64 v[32:33], s[4:5], 0, v[138:139]
	v_cndmask_b32_e32 v2, v0, v2, vcc
	v_lshlrev_b32_e32 v68, 2, v2
	v_xor_b32_e32 v2, 32, v0
	v_cmp_lt_i32_e32 vcc, v2, v1
	v_mov_b32_e32 v1, v137
	v_lshl_add_u64 v[34:35], s[6:7], 0, v[138:139]
	v_cndmask_b32_e32 v0, v0, v2, vcc
	v_lshlrev_b32_e32 v69, 2, v0
	v_or_b32_e32 v0, 0x1000, v138
	v_lshl_add_u64 v[36:37], s[4:5], 0, v[0:1]
	v_lshl_add_u64 v[38:39], s[6:7], 0, v[0:1]
	v_or_b32_e32 v0, 0x1800, v138
	v_lshl_add_u64 v[40:41], s[4:5], 0, v[0:1]
	v_lshl_add_u64 v[42:43], s[6:7], 0, v[0:1]
	v_lshl_add_u64 v[0:1], s[0:1], 0, v[138:139]
	s_mov_b64 s[0:1], 0x1000
	v_lshl_add_u64 v[44:45], v[0:1], 0, s[0:1]
	s_add_i32 s0, s38, s56
	s_ashr_i32 s1, s0, 31
	s_lshl_b64 s[4:5], s[56:57], 13
	s_lshl_b64 s[0:1], s[0:1], 12
	s_add_u32 s0, s42, s0
	s_addc_u32 s1, s43, s1
	v_lshl_add_u64 v[0:1], s[0:1], 0, v[136:137]
	s_mov_b64 s[0:1], 0x35800000
	v_lshl_add_u64 v[46:47], v[0:1], 0, s[0:1]
	s_lshl_b64 s[6:7], s[56:57], 12
	v_mov_b32_e32 v70, 0x3727c5ac
	s_mov_b32 s10, 0xf800000
	v_mov_b32_e32 v71, 0x260
	global_load_dwordx4 v[176:179], v[32:33], off
	global_load_dwordx4 v[184:187], v[34:35], off
	global_load_dwordx4 v[180:183], v[32:33], off offset:16
	global_load_dwordx4 v[188:191], v[34:35], off offset:16
	global_load_dwordx4 v[192:195], v[32:33], off offset:2048
	global_load_dwordx4 v[200:203], v[34:35], off offset:2048
	global_load_dwordx4 v[196:199], v[32:33], off offset:2064
	global_load_dwordx4 v[204:207], v[34:35], off offset:2064
	global_load_dwordx4 v[208:211], v[36:37], off
	global_load_dwordx4 v[216:219], v[38:39], off
	global_load_dwordx4 v[212:215], v[36:37], off offset:16
	global_load_dwordx4 v[220:223], v[38:39], off offset:16
	global_load_dwordx4 v[224:227], v[40:41], off
	global_load_dwordx4 v[232:235], v[42:43], off
	global_load_dwordx4 v[228:231], v[40:41], off offset:16
	global_load_dwordx4 v[236:239], v[42:43], off offset:16
	s_mov_b32 s98, 0
	s_add_i32 s99, s38, s56
	s_cmpk_gt_i32 s99, 0x7fff
	s_cbranch_scc1 .Lln3_pre_done
	global_load_dwordx4 v[0:3], v[46:47], off nt
	global_load_dwordx4 v[4:7], v[46:47], off offset:1024 nt
	global_load_dwordx4 v[8:11], v[46:47], off offset:2048 nt
	global_load_dwordx4 v[12:15], v[46:47], off offset:3072 nt
	v_lshl_add_u64 v[46:47], v[46:47], 0, s[6:7]

; __device__ __forceinline__ float bflo(unsigned w) { return __uint_as_float(w << 16); }
; __device__ __forceinline__ float bfhi(unsigned w) { return __uint_as_float(w & 0xffff0000u); }
; __device__ __forceinline__ void ln_rows(const bf16* Yb, const float* g, const float* bt, float* outf, bf16* outb, int gw, int NGW, int lane) {
;     ...
;     for (int row = gw; row < M; row += NGW) {
;         float v[4][8]; float s = 0.f;
; #pragma unroll
;         for (int j = 0; j < 4; ++j) { const u32x4 w = nx[j]; v[j][0] = bflo(w.x); v[j][1] = bfhi(w.x); v[j][2] = bflo(w.y); v[j][3] = bfhi(w.y); v[j][4] = bflo(w.z); v[j][5] = bfhi(w.z); v[j][6] = bflo(w.w); v[j][7] = bfhi(w.w);
;             s += ((v[j][0] + v[j][1]) + (v[j][2] + v[j][3])) + ((v[j][4] + v[j][5]) + (v[j][6] + v[j][7])); }
;         if (row + NGW < M) { const u32x4* yr = (const u32x4*)(Yb + (size_t)(row + NGW) * D) + lane;
; #pragma unroll
;             for (int j = 0; j < 4; ++j) nx[j] = yr[64 * j]; }
.LBB0_808:
	s_add_i32 s38, s38, s56
	s_cmpk_gt_i32 s38, 0x7fff
	s_cselect_b64 s[8:9], -1, 0
	s_xor_b32 s98, s98, 1
	s_add_i32 s99, s38, s56
	s_cmpk_gt_i32 s99, 0x7fff
	s_cbranch_scc1 .LBB0_810
	s_cmp_eq_u32 s98, 0
	s_cbranch_scc1 .Lln3_pfN1
	global_load_dwordx4 v[108:111], v[46:47], off nt
	global_load_dwordx4 v[112:115], v[46:47], off offset:1024 nt
	global_load_dwordx4 v[116:119], v[46:47], off offset:2048 nt
	global_load_dwordx4 v[120:123], v[46:47], off offset:3072 nt
	s_branch .LBB0_810
.Lln3_pfN1:
	global_load_dwordx4 v[0:3], v[46:47], off nt
	global_load_dwordx4 v[4:7], v[46:47], off offset:1024 nt
	global_load_dwordx4 v[8:11], v[46:47], off offset:2048 nt
	global_load_dwordx4 v[12:15], v[46:47], off offset:3072 nt
